# NSA selected and sliding-window loops: register-to-LDS copy of the next K/V tile (and its vmcnt waits) deferred from after QK^T to the end of the iteration
# speedup vs baseline: 1.0070x; 1.0008x over previous
.LBB0_758:
.LBB0_762:
	v_exp_f32_e32 v2, v120
	v_exp_f32_e32 v3, v121
	v_exp_f32_e32 v112, v112
	v_exp_f32_e32 v113, v113
	v_exp_f32_e32 v120, v122
	v_exp_f32_e32 v121, v123
	v_exp_f32_e32 v122, v132
	v_exp_f32_e32 v123, v133
	v_exp_f32_e32 v132, v134
	v_exp_f32_e32 v133, v135
	v_exp_f32_e32 v116, v116
	v_exp_f32_e32 v117, v117
	v_exp_f32_e32 v118, v118
	v_exp_f32_e32 v119, v119
	v_exp_f32_e32 v134, v114
	v_exp_f32_e32 v135, v115
	v_exp_f32_e32 v140, v140
	v_exp_f32_e32 v141, v141
	v_exp_f32_e32 v142, v142
	v_exp_f32_e32 v143, v143
	v_exp_f32_e32 v136, v136
	v_exp_f32_e32 v137, v137
	v_exp_f32_e32 v138, v138
	v_exp_f32_e32 v139, v139
	v_exp_f32_e32 v155, v124
	v_exp_f32_e32 v177, v125
	v_exp_f32_e32 v178, v126
	v_exp_f32_e32 v179, v127
	v_exp_f32_e32 v180, v128
	v_exp_f32_e32 v181, v129
	v_exp_f32_e32 v182, v130
	v_exp_f32_e32 v183, v131
	v_cvt_pk_bf16_f32 v114, v2, v3
	v_add3_u32 v3, s75, v167, v168
	v_cvt_pk_bf16_f32 v115, v120, v121
	v_cvt_pk_bf16_f32 v120, v112, v113
	v_lshl_add_u32 v112, v169, 1, v3
	v_lshl_add_u32 v113, v170, 1, v3
	v_cvt_pk_bf16_f32 v116, v116, v117
	v_cvt_pk_bf16_f32 v117, v118, v119
	v_cvt_pk_bf16_f32 v118, v122, v123
	v_cvt_pk_bf16_f32 v119, v132, v133
	v_cvt_pk_bf16_f32 v121, v134, v135
	ds_read_b64 v[130:131], v112 offset:8192
	ds_read_b64 v[132:133], v113 offset:8192
	ds_read_b64 v[126:127], v112 offset:10240
	ds_read_b64 v[128:129], v113 offset:10240
	v_lshl_add_u32 v2, v171, 1, v3
	v_lshl_add_u32 v3, v172, 1, v3
	s_andn2_b64 vcc, exec, s[34:35]
	s_waitcnt lgkmcnt(2)
	v_mfma_f32_16x16x32_bf16 v[52:55], v[130:133], v[114:117], v[52:55]
	v_mfma_f32_16x16x32_bf16 v[40:43], v[130:133], v[118:121], v[40:43]
	ds_read_b64 v[122:123], v112 offset:12288
	ds_read_b64 v[124:125], v113 offset:12288
	ds_read_b64 v[130:131], v112 offset:14336
	ds_read_b64 v[132:133], v113 offset:14336
	s_waitcnt lgkmcnt(4)
	v_mfma_f32_16x16x32_bf16 v[48:51], v[126:129], v[114:117], v[48:51]
	v_mfma_f32_16x16x32_bf16 v[32:35], v[126:129], v[118:121], v[32:35]
	s_waitcnt lgkmcnt(2)
	v_mfma_f32_16x16x32_bf16 v[44:47], v[122:125], v[114:117], v[44:47]
	ds_read_b64 v[126:127], v2 offset:8192
	ds_read_b64 v[128:129], v3 offset:8192
	v_mfma_f32_16x16x32_bf16 v[28:31], v[122:125], v[118:121], v[28:31]
	s_waitcnt lgkmcnt(2)
	v_mfma_f32_16x16x32_bf16 v[36:39], v[130:133], v[114:117], v[36:39]
	v_mfma_f32_16x16x32_bf16 v[24:27], v[130:133], v[118:121], v[24:27]
	ds_read_b64 v[122:123], v2 offset:10240
	ds_read_b64 v[124:125], v3 offset:10240
	v_mfma_f32_16x16x32_bf16 v[72:75], v[20:23], v[114:117], v[72:75]
	v_cvt_pk_bf16_f32 v114, v140, v141
	v_cvt_pk_bf16_f32 v115, v142, v143
	v_cvt_pk_bf16_f32 v116, v155, v177
	v_mfma_f32_16x16x32_bf16 v[76:79], v[20:23], v[118:121], v[76:79]
	v_cvt_pk_bf16_f32 v117, v178, v179
	v_cvt_pk_bf16_f32 v118, v136, v137
	v_cvt_pk_bf16_f32 v119, v138, v139
	v_cvt_pk_bf16_f32 v120, v180, v181
	v_cvt_pk_bf16_f32 v121, v182, v183
	s_waitcnt lgkmcnt(2)
	s_nop 0
	v_mfma_f32_16x16x32_bf16 v[52:55], v[126:129], v[114:117], v[52:55]
	v_mfma_f32_16x16x32_bf16 v[40:43], v[126:129], v[118:121], v[40:43]
	ds_read_b64 v[130:131], v2 offset:12288
	ds_read_b64 v[132:133], v3 offset:12288
	ds_read_b64 v[126:127], v2 offset:14336
	ds_read_b64 v[128:129], v3 offset:14336
	s_waitcnt lgkmcnt(4)
	v_mfma_f32_16x16x32_bf16 v[48:51], v[122:125], v[114:117], v[48:51]
	v_mfma_f32_16x16x32_bf16 v[32:35], v[122:125], v[118:121], v[32:35]
	v_mfma_f32_16x16x32_bf16 v[72:75], v[20:23], v[114:117], v[72:75]
	v_mfma_f32_16x16x32_bf16 v[76:79], v[20:23], v[118:121], v[76:79]
	s_waitcnt lgkmcnt(2)
	v_mfma_f32_16x16x32_bf16 v[44:47], v[130:133], v[114:117], v[44:47]
	v_mfma_f32_16x16x32_bf16 v[28:31], v[130:133], v[118:121], v[28:31]
	s_waitcnt lgkmcnt(0)
	v_mfma_f32_16x16x32_bf16 v[36:39], v[126:129], v[114:117], v[36:39]
	v_mfma_f32_16x16x32_bf16 v[24:27], v[126:129], v[118:121], v[24:27]
	s_cbranch_vccnz .LBB0_764
	ds_read_b64 v[130:131], v112 offset:24576
	ds_read_b64 v[132:133], v113 offset:24576
	ds_read_b64 v[126:127], v112 offset:26624
	ds_read_b64 v[128:129], v113 offset:26624
	v_exp_f32_e32 v88, v88
	v_exp_f32_e32 v89, v89
	v_exp_f32_e32 v90, v90
	v_exp_f32_e32 v91, v91
	v_exp_f32_e32 v100, v100
	v_exp_f32_e32 v101, v101
	v_exp_f32_e32 v102, v102
	v_exp_f32_e32 v103, v103
	v_exp_f32_e32 v84, v84
	v_exp_f32_e32 v85, v85
	v_exp_f32_e32 v86, v86
	v_exp_f32_e32 v87, v87
	v_exp_f32_e32 v80, v80
	v_exp_f32_e32 v81, v81
	v_exp_f32_e32 v82, v82
	v_exp_f32_e32 v83, v83
	v_cvt_pk_bf16_f32 v114, v88, v89
	v_cvt_pk_bf16_f32 v115, v90, v91
	v_cvt_pk_bf16_f32 v116, v84, v85
	v_cvt_pk_bf16_f32 v117, v86, v87
	v_cvt_pk_bf16_f32 v118, v100, v101
	v_cvt_pk_bf16_f32 v119, v102, v103
	v_cvt_pk_bf16_f32 v120, v80, v81
	v_cvt_pk_bf16_f32 v121, v82, v83
	s_waitcnt lgkmcnt(2)
	s_nop 0
	v_mfma_f32_16x16x32_bf16 v[52:55], v[130:133], v[114:117], v[52:55]
	v_mfma_f32_16x16x32_bf16 v[40:43], v[130:133], v[118:121], v[40:43]
	ds_read_b64 v[134:135], v112 offset:28672
	ds_read_b64 v[136:137], v113 offset:28672
	ds_read_b64 v[122:123], v112 offset:30720
	ds_read_b64 v[124:125], v113 offset:30720
	v_exp_f32_e32 v108, v108
	v_exp_f32_e32 v109, v109
	v_mfma_f32_16x16x32_bf16 v[76:79], v[20:23], v[118:121], v[76:79]
	v_exp_f32_e32 v110, v110
	v_exp_f32_e32 v111, v111
	v_exp_f32_e32 v104, v104
	s_waitcnt lgkmcnt(4)
	v_mfma_f32_16x16x32_bf16 v[48:51], v[126:129], v[114:117], v[48:51]
	v_exp_f32_e32 v105, v105
	v_exp_f32_e32 v106, v106
	v_exp_f32_e32 v107, v107
	v_mfma_f32_16x16x32_bf16 v[32:35], v[126:129], v[118:121], v[32:35]
	ds_read_b64 v[130:131], v2 offset:24576
	ds_read_b64 v[132:133], v3 offset:24576
	v_exp_f32_e32 v92, v92
	v_exp_f32_e32 v93, v93
	s_waitcnt lgkmcnt(4)
	v_mfma_f32_16x16x32_bf16 v[28:31], v[134:137], v[118:121], v[28:31]
	v_exp_f32_e32 v94, v94
	v_exp_f32_e32 v95, v95
	v_exp_f32_e32 v96, v96
	s_waitcnt lgkmcnt(2)
	v_mfma_f32_16x16x32_bf16 v[24:27], v[122:125], v[118:121], v[24:27]
	ds_read_b64 v[126:127], v2 offset:26624
	ds_read_b64 v[128:129], v3 offset:26624
	v_exp_f32_e32 v97, v97
	v_exp_f32_e32 v98, v98
	v_mfma_f32_16x16x32_bf16 v[36:39], v[122:125], v[114:117], v[36:39]
	v_exp_f32_e32 v99, v99
	v_mfma_f32_16x16x32_bf16 v[72:75], v[20:23], v[114:117], v[72:75]
	v_cvt_pk_bf16_f32 v112, v108, v109
	v_cvt_pk_bf16_f32 v113, v110, v111
	v_cvt_pk_bf16_f32 v118, v96, v97
	v_mfma_f32_16x16x32_bf16 v[44:47], v[134:137], v[114:117], v[44:47]
	v_cvt_pk_bf16_f32 v114, v92, v93
	v_cvt_pk_bf16_f32 v115, v94, v95
	v_cvt_pk_bf16_f32 v116, v104, v105
	v_cvt_pk_bf16_f32 v117, v106, v107
	v_cvt_pk_bf16_f32 v119, v98, v99
	s_waitcnt lgkmcnt(2)
	s_nop 0
	v_mfma_f32_16x16x32_bf16 v[52:55], v[130:133], v[112:115], v[52:55]
	v_mfma_f32_16x16x32_bf16 v[40:43], v[130:133], v[116:119], v[40:43]
	ds_read_b64 v[122:123], v2 offset:28672
	ds_read_b64 v[124:125], v3 offset:28672
	ds_read_b64 v[134:135], v2 offset:30720
	ds_read_b64 v[136:137], v3 offset:30720
	s_waitcnt lgkmcnt(4)
	v_mfma_f32_16x16x32_bf16 v[48:51], v[126:129], v[112:115], v[48:51]
	v_mfma_f32_16x16x32_bf16 v[32:35], v[126:129], v[116:119], v[32:35]
	v_mfma_f32_16x16x32_bf16 v[72:75], v[20:23], v[112:115], v[72:75]
	v_mfma_f32_16x16x32_bf16 v[76:79], v[20:23], v[116:119], v[76:79]
	s_waitcnt lgkmcnt(2)
	v_mfma_f32_16x16x32_bf16 v[44:47], v[122:125], v[112:115], v[44:47]
	v_mfma_f32_16x16x32_bf16 v[28:31], v[122:125], v[116:119], v[28:31]
	s_waitcnt lgkmcnt(0)
	v_mfma_f32_16x16x32_bf16 v[36:39], v[134:137], v[112:115], v[36:39]
	v_mfma_f32_16x16x32_bf16 v[24:27], v[134:137], v[116:119], v[24:27]

.Llatew_s2:
	s_waitcnt lgkmcnt(0)
	s_and_b32 s5, s74, s72
	s_and_b64 s[6:7], exec, s[28:29]
	v_readfirstlane_b32 s4, v0
	s_cselect_b32 s76, -1, s73
	s_andn2_b64 vcc, exec, s[26:27]
	s_xor_b32 s70, s70, s4
	s_barrier
	s_cbranch_vccz .LBB0_766
	s_mov_b32 s4, s71
	s_branch .LBB0_749

.LBB0_780:
.LBB0_784:
	v_exp_f32_e32 v2, v132
	v_exp_f32_e32 v3, v133
	v_exp_f32_e32 v116, v116
	v_exp_f32_e32 v117, v117
	v_exp_f32_e32 v132, v134
	v_exp_f32_e32 v133, v135
	v_exp_f32_e32 v124, v124
	v_exp_f32_e32 v125, v125
	v_exp_f32_e32 v126, v126
	v_exp_f32_e32 v127, v127
	v_exp_f32_e32 v120, v120
	v_exp_f32_e32 v121, v121
	v_exp_f32_e32 v122, v122
	v_exp_f32_e32 v123, v123
	v_exp_f32_e32 v134, v118
	v_exp_f32_e32 v135, v119
	v_exp_f32_e32 v174, v136
	v_exp_f32_e32 v177, v137
	v_exp_f32_e32 v138, v138
	v_exp_f32_e32 v139, v139
	v_exp_f32_e32 v178, v128
	v_exp_f32_e32 v179, v129
	v_exp_f32_e32 v180, v130
	v_exp_f32_e32 v181, v131
	v_exp_f32_e32 v140, v140
	v_exp_f32_e32 v141, v141
	v_exp_f32_e32 v142, v142
	v_exp_f32_e32 v143, v143
	v_exp_f32_e32 v144, v144
	v_exp_f32_e32 v145, v145
	v_exp_f32_e32 v146, v146
	v_exp_f32_e32 v147, v147
	v_cvt_pk_bf16_f32 v118, v2, v3
	v_add3_u32 v3, s75, v167, v168
	v_cvt_pk_bf16_f32 v120, v120, v121
	v_cvt_pk_bf16_f32 v121, v122, v123
	v_cvt_pk_bf16_f32 v122, v124, v125
	v_cvt_pk_bf16_f32 v124, v116, v117
	v_lshl_add_u32 v116, v169, 1, v3
	v_lshl_add_u32 v117, v170, 1, v3
	v_cvt_pk_bf16_f32 v119, v132, v133
	v_cvt_pk_bf16_f32 v123, v126, v127
	v_cvt_pk_bf16_f32 v125, v134, v135
	v_lshl_add_u32 v2, v171, 1, v3
	v_lshl_add_u32 v3, v172, 1, v3
	s_andn2_b64 vcc, exec, s[30:31]
	ds_read_b64 v[134:135], v116 offset:8192
	ds_read_b64 v[136:137], v117 offset:8192
	ds_read_b64 v[130:131], v116 offset:10240
	ds_read_b64 v[132:133], v117 offset:10240
	s_waitcnt lgkmcnt(2)
	s_nop 0
	v_mfma_f32_16x16x32_bf16 v[72:75], v[134:137], v[118:121], v[72:75]
	v_mfma_f32_16x16x32_bf16 v[36:39], v[134:137], v[122:125], v[36:39]
	ds_read_b64 v[126:127], v116 offset:12288
	ds_read_b64 v[128:129], v117 offset:12288
	ds_read_b64 v[134:135], v116 offset:14336
	ds_read_b64 v[136:137], v117 offset:14336
	s_waitcnt lgkmcnt(4)
	v_mfma_f32_16x16x32_bf16 v[68:71], v[130:133], v[118:121], v[68:71]
	v_mfma_f32_16x16x32_bf16 v[32:35], v[130:133], v[122:125], v[32:35]
	s_waitcnt lgkmcnt(2)
	v_mfma_f32_16x16x32_bf16 v[64:67], v[126:129], v[118:121], v[64:67]
	ds_read_b64 v[130:131], v2 offset:8192
	ds_read_b64 v[132:133], v3 offset:8192
	v_mfma_f32_16x16x32_bf16 v[28:31], v[126:129], v[122:125], v[28:31]
	s_waitcnt lgkmcnt(2)
	v_mfma_f32_16x16x32_bf16 v[56:59], v[134:137], v[118:121], v[56:59]
	v_mfma_f32_16x16x32_bf16 v[24:27], v[134:137], v[122:125], v[24:27]
	ds_read_b64 v[126:127], v2 offset:10240
	ds_read_b64 v[128:129], v3 offset:10240
	v_mfma_f32_16x16x32_bf16 v[112:115], v[20:23], v[118:121], v[112:115]
	v_cvt_pk_bf16_f32 v118, v174, v177
	v_cvt_pk_bf16_f32 v119, v138, v139
	v_cvt_pk_bf16_f32 v120, v140, v141
	v_mfma_f32_16x16x32_bf16 v[76:79], v[20:23], v[122:125], v[76:79]
	v_cvt_pk_bf16_f32 v121, v142, v143
	v_cvt_pk_bf16_f32 v122, v178, v179
	v_cvt_pk_bf16_f32 v123, v180, v181
	v_cvt_pk_bf16_f32 v124, v144, v145
	v_cvt_pk_bf16_f32 v125, v146, v147
	s_waitcnt lgkmcnt(2)
	s_nop 0
	v_mfma_f32_16x16x32_bf16 v[72:75], v[130:133], v[118:121], v[72:75]
	v_mfma_f32_16x16x32_bf16 v[36:39], v[130:133], v[122:125], v[36:39]
	ds_read_b64 v[134:135], v2 offset:12288
	ds_read_b64 v[136:137], v3 offset:12288
	ds_read_b64 v[130:131], v2 offset:14336
	ds_read_b64 v[132:133], v3 offset:14336
	s_waitcnt lgkmcnt(4)
	v_mfma_f32_16x16x32_bf16 v[68:71], v[126:129], v[118:121], v[68:71]
	v_mfma_f32_16x16x32_bf16 v[32:35], v[126:129], v[122:125], v[32:35]
	v_mfma_f32_16x16x32_bf16 v[112:115], v[20:23], v[118:121], v[112:115]
	v_mfma_f32_16x16x32_bf16 v[76:79], v[20:23], v[122:125], v[76:79]
	s_waitcnt lgkmcnt(2)
	v_mfma_f32_16x16x32_bf16 v[64:67], v[134:137], v[118:121], v[64:67]
	v_mfma_f32_16x16x32_bf16 v[28:31], v[134:137], v[122:125], v[28:31]
	s_waitcnt lgkmcnt(0)
	v_mfma_f32_16x16x32_bf16 v[56:59], v[130:133], v[118:121], v[56:59]
	v_mfma_f32_16x16x32_bf16 v[24:27], v[130:133], v[122:125], v[24:27]
	s_cbranch_vccnz .LBB0_786
	ds_read_b64 v[134:135], v116 offset:24576
	ds_read_b64 v[136:137], v117 offset:24576
	ds_read_b64 v[130:131], v116 offset:26624
	ds_read_b64 v[132:133], v117 offset:26624
	v_exp_f32_e32 v96, v96
	v_exp_f32_e32 v97, v97
	v_exp_f32_e32 v98, v98
	v_exp_f32_e32 v99, v99
	v_exp_f32_e32 v88, v88
	v_exp_f32_e32 v89, v89
	v_exp_f32_e32 v90, v90
	v_exp_f32_e32 v91, v91
	v_exp_f32_e32 v84, v84
	v_exp_f32_e32 v85, v85
	v_exp_f32_e32 v86, v86
	v_exp_f32_e32 v87, v87
	v_exp_f32_e32 v80, v80
	v_exp_f32_e32 v81, v81
	v_exp_f32_e32 v82, v82
	v_exp_f32_e32 v83, v83
	v_cvt_pk_bf16_f32 v118, v96, v97
	v_cvt_pk_bf16_f32 v119, v98, v99
	v_cvt_pk_bf16_f32 v120, v84, v85
	v_cvt_pk_bf16_f32 v121, v86, v87
	v_cvt_pk_bf16_f32 v122, v88, v89
	v_cvt_pk_bf16_f32 v123, v90, v91
	v_cvt_pk_bf16_f32 v124, v80, v81
	v_cvt_pk_bf16_f32 v125, v82, v83
	s_waitcnt lgkmcnt(2)
	s_nop 0
	v_mfma_f32_16x16x32_bf16 v[72:75], v[134:137], v[118:121], v[72:75]
	v_mfma_f32_16x16x32_bf16 v[36:39], v[134:137], v[122:125], v[36:39]
	ds_read_b64 v[138:139], v116 offset:28672
	ds_read_b64 v[140:141], v117 offset:28672
	ds_read_b64 v[126:127], v116 offset:30720
	ds_read_b64 v[128:129], v117 offset:30720
	v_exp_f32_e32 v100, v100
	v_exp_f32_e32 v101, v101
	v_mfma_f32_16x16x32_bf16 v[76:79], v[20:23], v[122:125], v[76:79]
	v_exp_f32_e32 v102, v102
	v_exp_f32_e32 v103, v103
	v_exp_f32_e32 v92, v92
	s_waitcnt lgkmcnt(4)
	v_mfma_f32_16x16x32_bf16 v[68:71], v[130:133], v[118:121], v[68:71]
	v_exp_f32_e32 v93, v93
	v_exp_f32_e32 v94, v94
	v_exp_f32_e32 v95, v95
	v_mfma_f32_16x16x32_bf16 v[32:35], v[130:133], v[122:125], v[32:35]
	ds_read_b64 v[134:135], v2 offset:24576
	ds_read_b64 v[136:137], v3 offset:24576
	v_exp_f32_e32 v104, v104
	v_exp_f32_e32 v105, v105
	s_waitcnt lgkmcnt(4)
	v_mfma_f32_16x16x32_bf16 v[28:31], v[138:141], v[122:125], v[28:31]
	v_exp_f32_e32 v106, v106
	v_exp_f32_e32 v107, v107
	v_exp_f32_e32 v108, v108
	s_waitcnt lgkmcnt(2)
	v_mfma_f32_16x16x32_bf16 v[24:27], v[126:129], v[122:125], v[24:27]
	ds_read_b64 v[130:131], v2 offset:26624
	ds_read_b64 v[132:133], v3 offset:26624
	v_exp_f32_e32 v109, v109
	v_exp_f32_e32 v110, v110
	v_mfma_f32_16x16x32_bf16 v[56:59], v[126:129], v[118:121], v[56:59]
	v_exp_f32_e32 v111, v111
	v_mfma_f32_16x16x32_bf16 v[112:115], v[20:23], v[118:121], v[112:115]
	v_cvt_pk_bf16_f32 v116, v100, v101
	v_cvt_pk_bf16_f32 v117, v102, v103
	v_cvt_pk_bf16_f32 v122, v108, v109
	v_mfma_f32_16x16x32_bf16 v[64:67], v[138:141], v[118:121], v[64:67]
	v_cvt_pk_bf16_f32 v118, v104, v105
	v_cvt_pk_bf16_f32 v119, v106, v107
	v_cvt_pk_bf16_f32 v120, v92, v93
	v_cvt_pk_bf16_f32 v121, v94, v95
	v_cvt_pk_bf16_f32 v123, v110, v111
	s_waitcnt lgkmcnt(2)
	s_nop 0
	v_mfma_f32_16x16x32_bf16 v[72:75], v[134:137], v[116:119], v[72:75]
	v_mfma_f32_16x16x32_bf16 v[36:39], v[134:137], v[120:123], v[36:39]
	ds_read_b64 v[126:127], v2 offset:28672
	ds_read_b64 v[128:129], v3 offset:28672
	ds_read_b64 v[138:139], v2 offset:30720
	ds_read_b64 v[140:141], v3 offset:30720
	s_waitcnt lgkmcnt(4)
	v_mfma_f32_16x16x32_bf16 v[68:71], v[130:133], v[116:119], v[68:71]
	v_mfma_f32_16x16x32_bf16 v[32:35], v[130:133], v[120:123], v[32:35]
	v_mfma_f32_16x16x32_bf16 v[112:115], v[20:23], v[116:119], v[112:115]
	v_mfma_f32_16x16x32_bf16 v[76:79], v[20:23], v[120:123], v[76:79]
	s_waitcnt lgkmcnt(2)
	v_mfma_f32_16x16x32_bf16 v[64:67], v[126:129], v[116:119], v[64:67]
	v_mfma_f32_16x16x32_bf16 v[28:31], v[126:129], v[120:123], v[28:31]
	s_waitcnt lgkmcnt(0)
	v_mfma_f32_16x16x32_bf16 v[56:59], v[138:141], v[116:119], v[56:59]
	v_mfma_f32_16x16x32_bf16 v[24:27], v[138:141], v[120:123], v[24:27]

.Llatew_w2:
	s_waitcnt lgkmcnt(0)
	s_and_b32 s5, s74, s72
	s_and_b64 s[6:7], exec, s[26:27]
	v_readfirstlane_b32 s4, v0
	s_cselect_b32 s76, -1, s73
	s_andn2_b64 vcc, exec, s[24:25]
	s_xor_b32 s70, s70, s4
	s_barrier
	s_cbranch_vccz .LBB0_722
	s_mov_b32 s4, s71
	s_branch .LBB0_771
